# v65 + XCD-local barriers: spinners poll the arrival counter (exit at count >= target) instead of the generation word bumped one atomic round trip later; global sites spin while gen word <= gen
# speedup vs baseline: 1.0084x; 1.0054x over previous
; __device__ __forceinline__ unsigned xb_ld(unsigned* p)              { return __hip_atomic_load(p, __ATOMIC_RELAXED, __HIP_MEMORY_SCOPE_AGENT); }
; __device__ __forceinline__ unsigned xb_add(unsigned* p, unsigned v) { return __hip_atomic_fetch_add(p, v, __ATOMIC_RELAXED, __HIP_MEMORY_SCOPE_AGENT); }
; #define XB_SPIN(cond, bar) do { unsigned _sp = 0; while (cond) { __builtin_amdgcn_s_sleep(1); \
;     if ((++_sp & 255u) == 0u) { if (xb_ld(&(bar)[XB_TMO])) break; if (_sp > XB_SPIN_CAP) { atomicAdd(&(bar)[XB_TMO], 1u); break; } } } } while (0)
; __device__ __forceinline__ void xcd_barrier(const XcdBarrier& b, bool local = false) {
;     ...
;         const unsigned old = xb_add(&bar[XB_XSUB(b.x)], 1u);
;         const unsigned gen = old / nloc;
;         if (old + 1u == (gen + 1u) * nloc) {
;             if (!local) {
;             __builtin_amdgcn_fence(__ATOMIC_RELEASE, "agent");
;             asm volatile("s_waitcnt vmcnt(0)" ::: "memory");
;             const unsigned og = xb_add(&bar[XB_TOP], 1u);
;             const unsigned tg = og / nx;
;             if (og + 1u == (tg + 1u) * nx) xb_add(&bar[XB_TOPGEN], 1u);
;             else XB_SPIN(xb_ld(&bar[XB_TOPGEN]) == tg, bar);
;             }
;             __builtin_amdgcn_fence(__ATOMIC_ACQUIRE, "agent");
;             xb_add(&bar[XB_XGEN(b.x)], 1u);
;             asm volatile("s_waitcnt vmcnt(0)" ::: "memory");
;         } else {
;             XB_SPIN(xb_ld(&bar[XB_XGEN(b.x)]) == gen, bar);
;             __builtin_amdgcn_fence(__ATOMIC_ACQUIRE, "agent");
.LBB0_290:
	s_or_b64 exec, exec, s[4:5]
	v_cvt_f32_u32_e32 v5, v3
	s_waitcnt vmcnt(0)
	v_readfirstlane_b32 s4, v4
	v_sub_u32_e32 v4, 0, v3
	v_rcp_iflag_f32_e32 v5, v5
	v_add_u32_e32 v6, s4, v1
	v_mul_f32_e32 v5, 0x4f7ffffe, v5
	v_cvt_u32_f32_e32 v5, v5
	v_mul_lo_u32 v1, v4, v5
	v_mul_hi_u32 v1, v5, v1
	v_add_u32_e32 v1, v5, v1
	v_mul_hi_u32 v1, v6, v1
	v_mul_lo_u32 v4, v1, v3
	v_sub_u32_e32 v4, v6, v4
	v_add_u32_e32 v5, 1, v1
	v_cmp_ge_u32_e32 vcc, v4, v3
	s_nop 1
	v_cndmask_b32_e32 v1, v1, v5, vcc
	v_sub_u32_e32 v5, v4, v3
	v_cndmask_b32_e32 v4, v4, v5, vcc
	v_add_u32_e32 v5, 1, v1
	v_cmp_ge_u32_e32 vcc, v4, v3
	v_add_u32_e32 v4, 1, v6
	s_nop 0
	v_cndmask_b32_e32 v1, v1, v5, vcc
	v_mul_lo_u32 v5, v3, v1
	v_add_u32_e32 v3, v5, v3
	v_cmp_ne_u32_e32 vcc, v4, v3
	s_and_saveexec_b64 s[4:5], vcc
	s_xor_b64 s[4:5], exec, s[4:5]
	s_cbranch_execz .LBB0_304
	v_readlane_b32 s6, v253, 61
	v_readlane_b32 s7, v253, 62
	s_waitcnt lgkmcnt(0)
	s_nop 3
	global_load_dword v2, v0, s[6:7] sc1
	s_waitcnt vmcnt(0)
	v_cmp_le_u32_e32 vcc, v2, v1
	s_and_saveexec_b64 s[6:7], vcc
	s_cbranch_execz .LBB0_303
	s_mov_b32 s16, 1
	s_mov_b64 s[8:9], 0
	s_branch .LBB0_294

; __device__ __forceinline__ unsigned xb_ld(unsigned* p)              { return __hip_atomic_load(p, __ATOMIC_RELAXED, __HIP_MEMORY_SCOPE_AGENT); }
; #define XB_SPIN(cond, bar) do { unsigned _sp = 0; while (cond) { __builtin_amdgcn_s_sleep(1); \
;     if ((++_sp & 255u) == 0u) { if (xb_ld(&(bar)[XB_TMO])) break; if (_sp > XB_SPIN_CAP) { atomicAdd(&(bar)[XB_TMO], 1u); break; } } } } while (0)
; __device__ __forceinline__ void xcd_barrier(const XcdBarrier& b, bool local = false) {
;     ...
;             XB_SPIN(xb_ld(&bar[XB_XGEN(b.x)]) == gen, bar);
.LBB0_298:
	v_readlane_b32 s18, v253, 61
	v_readlane_b32 s19, v253, 62
	s_add_i32 s16, s16, 1
	s_mov_b64 s[46:47], -1
	s_nop 2
	global_load_dword v2, v0, s[18:19] sc1
	s_waitcnt vmcnt(0)
	v_cmp_gt_u32_e32 vcc, v2, v1
	s_orn2_b64 s[44:45], vcc, exec
	s_branch .LBB0_293

; __device__ __forceinline__ unsigned xb_ld(unsigned* p)              { return __hip_atomic_load(p, __ATOMIC_RELAXED, __HIP_MEMORY_SCOPE_AGENT); }
; __device__ __forceinline__ unsigned xb_add(unsigned* p, unsigned v) { return __hip_atomic_fetch_add(p, v, __ATOMIC_RELAXED, __HIP_MEMORY_SCOPE_AGENT); }
; #define XB_SPIN(cond, bar) do { unsigned _sp = 0; while (cond) { __builtin_amdgcn_s_sleep(1); \
;     if ((++_sp & 255u) == 0u) { if (xb_ld(&(bar)[XB_TMO])) break; if (_sp > XB_SPIN_CAP) { atomicAdd(&(bar)[XB_TMO], 1u); break; } } } } while (0)
; __device__ __forceinline__ void xcd_barrier(const XcdBarrier& b, bool local = false) {
;     ...
;         const unsigned old = xb_add(&bar[XB_XSUB(b.x)], 1u);
;         const unsigned gen = old / nloc;
;         if (old + 1u == (gen + 1u) * nloc) {
;             if (!local) {
;             __builtin_amdgcn_fence(__ATOMIC_RELEASE, "agent");
;             asm volatile("s_waitcnt vmcnt(0)" ::: "memory");
;             const unsigned og = xb_add(&bar[XB_TOP], 1u);
;             const unsigned tg = og / nx;
;             if (og + 1u == (tg + 1u) * nx) xb_add(&bar[XB_TOPGEN], 1u);
;             else XB_SPIN(xb_ld(&bar[XB_TOPGEN]) == tg, bar);
;             }
;             __builtin_amdgcn_fence(__ATOMIC_ACQUIRE, "agent");
;             xb_add(&bar[XB_XGEN(b.x)], 1u);
;             asm volatile("s_waitcnt vmcnt(0)" ::: "memory");
;         } else {
;             XB_SPIN(xb_ld(&bar[XB_XGEN(b.x)]) == gen, bar);
;             __builtin_amdgcn_fence(__ATOMIC_ACQUIRE, "agent");
.LBB0_426:
	s_or_b64 exec, exec, s[4:5]
	v_cvt_f32_u32_e32 v5, v3
	s_waitcnt vmcnt(0)
	v_readfirstlane_b32 s4, v4
	v_sub_u32_e32 v4, 0, v3
	v_rcp_iflag_f32_e32 v5, v5
	v_add_u32_e32 v6, s4, v1
	v_mul_f32_e32 v5, 0x4f7ffffe, v5
	v_cvt_u32_f32_e32 v5, v5
	v_mul_lo_u32 v1, v4, v5
	v_mul_hi_u32 v1, v5, v1
	v_add_u32_e32 v1, v5, v1
	v_mul_hi_u32 v1, v6, v1
	v_mul_lo_u32 v4, v1, v3
	v_sub_u32_e32 v4, v6, v4
	v_add_u32_e32 v5, 1, v1
	v_cmp_ge_u32_e32 vcc, v4, v3
	s_nop 1
	v_cndmask_b32_e32 v1, v1, v5, vcc
	v_sub_u32_e32 v5, v4, v3
	v_cndmask_b32_e32 v4, v4, v5, vcc
	v_add_u32_e32 v5, 1, v1
	v_cmp_ge_u32_e32 vcc, v4, v3
	v_add_u32_e32 v4, 1, v6
	s_nop 0
	v_cndmask_b32_e32 v1, v1, v5, vcc
	v_mul_lo_u32 v5, v3, v1
	v_add_u32_e32 v3, v5, v3
	v_cmp_ne_u32_e32 vcc, v4, v3
	s_and_saveexec_b64 s[4:5], vcc
	s_xor_b64 s[4:5], exec, s[4:5]
	s_cbranch_execz .LBB0_440
	v_readlane_b32 s6, v253, 61
	v_readlane_b32 s7, v253, 62
	s_and_b64 vcc, exec, s[76:77]
	s_cbranch_vccz .Lxl0a
	v_readlane_b32 s6, v253, 59
	v_readlane_b32 s7, v253, 60
.Lxl0a:
	s_waitcnt lgkmcnt(0)
	s_nop 3
	global_load_dword v2, v0, s[6:7] sc1
	s_waitcnt vmcnt(0)
	s_and_b64 vcc, exec, s[76:77]
	s_cbranch_vccz .Lxl0b
	v_cmp_lt_u32_e32 vcc, v2, v3
	s_branch .Lxl0c
.Lxl0b:
	v_cmp_eq_u32_e32 vcc, v2, v1
.Lxl0c:
	s_and_saveexec_b64 s[6:7], vcc
	s_cbranch_execz .LBB0_439
	s_mov_b32 s16, 1
	s_mov_b64 s[8:9], 0
	s_branch .LBB0_430

; __device__ __forceinline__ unsigned xb_ld(unsigned* p)              { return __hip_atomic_load(p, __ATOMIC_RELAXED, __HIP_MEMORY_SCOPE_AGENT); }
; #define XB_SPIN(cond, bar) do { unsigned _sp = 0; while (cond) { __builtin_amdgcn_s_sleep(1); \
;     if ((++_sp & 255u) == 0u) { if (xb_ld(&(bar)[XB_TMO])) break; if (_sp > XB_SPIN_CAP) { atomicAdd(&(bar)[XB_TMO], 1u); break; } } } } while (0)
; __device__ __forceinline__ void xcd_barrier(const XcdBarrier& b, bool local = false) {
;     ...
;             XB_SPIN(xb_ld(&bar[XB_XGEN(b.x)]) == gen, bar);
.LBB0_434:
	v_readlane_b32 s18, v253, 61
	v_readlane_b32 s19, v253, 62
	s_and_b64 vcc, exec, s[76:77]
	s_cbranch_vccz .Lxl0d
	v_readlane_b32 s18, v253, 59
	v_readlane_b32 s19, v253, 60
.Lxl0d:
	s_add_i32 s16, s16, 1
	s_mov_b64 s[44:45], -1
	s_nop 2
	global_load_dword v2, v0, s[18:19] sc1
	s_waitcnt vmcnt(0)
	s_and_b64 vcc, exec, s[76:77]
	s_cbranch_vccz .Lxl0e
	v_cmp_ge_u32_e32 vcc, v2, v3
	s_branch .Lxl0f
.Lxl0e:
	v_cmp_ne_u32_e32 vcc, v2, v1
.Lxl0f:
	s_orn2_b64 s[42:43], vcc, exec
	s_branch .LBB0_429

; __device__ __forceinline__ unsigned xb_ld(unsigned* p)              { return __hip_atomic_load(p, __ATOMIC_RELAXED, __HIP_MEMORY_SCOPE_AGENT); }
; __device__ __forceinline__ unsigned xb_add(unsigned* p, unsigned v) { return __hip_atomic_fetch_add(p, v, __ATOMIC_RELAXED, __HIP_MEMORY_SCOPE_AGENT); }
; #define XB_SPIN(cond, bar) do { unsigned _sp = 0; while (cond) { __builtin_amdgcn_s_sleep(1); \
;     if ((++_sp & 255u) == 0u) { if (xb_ld(&(bar)[XB_TMO])) break; if (_sp > XB_SPIN_CAP) { atomicAdd(&(bar)[XB_TMO], 1u); break; } } } } while (0)
; __device__ __forceinline__ void xcd_barrier(const XcdBarrier& b, bool local = false) {
;     ...
;         const unsigned old = xb_add(&bar[XB_XSUB(b.x)], 1u);
;         const unsigned gen = old / nloc;
;         if (old + 1u == (gen + 1u) * nloc) {
;             if (!local) {
;             __builtin_amdgcn_fence(__ATOMIC_RELEASE, "agent");
;             asm volatile("s_waitcnt vmcnt(0)" ::: "memory");
;             const unsigned og = xb_add(&bar[XB_TOP], 1u);
;             const unsigned tg = og / nx;
;             if (og + 1u == (tg + 1u) * nx) xb_add(&bar[XB_TOPGEN], 1u);
;             else XB_SPIN(xb_ld(&bar[XB_TOPGEN]) == tg, bar);
;             }
;             __builtin_amdgcn_fence(__ATOMIC_ACQUIRE, "agent");
;             xb_add(&bar[XB_XGEN(b.x)], 1u);
;             asm volatile("s_waitcnt vmcnt(0)" ::: "memory");
;         } else {
;             XB_SPIN(xb_ld(&bar[XB_XGEN(b.x)]) == gen, bar);
;             __builtin_amdgcn_fence(__ATOMIC_ACQUIRE, "agent");
.LBB0_842:
	s_or_b64 exec, exec, s[4:5]
	v_cvt_f32_u32_e32 v5, v3
	s_waitcnt vmcnt(0)
	v_readfirstlane_b32 s4, v4
	v_sub_u32_e32 v4, 0, v3
	v_rcp_iflag_f32_e32 v5, v5
	v_add_u32_e32 v6, s4, v1
	v_mul_f32_e32 v5, 0x4f7ffffe, v5
	v_cvt_u32_f32_e32 v5, v5
	v_mul_lo_u32 v1, v4, v5
	v_mul_hi_u32 v1, v5, v1
	v_add_u32_e32 v1, v5, v1
	v_mul_hi_u32 v1, v6, v1
	v_mul_lo_u32 v4, v1, v3
	v_sub_u32_e32 v4, v6, v4
	v_add_u32_e32 v5, 1, v1
	v_cmp_ge_u32_e32 vcc, v4, v3
	s_nop 1
	v_cndmask_b32_e32 v1, v1, v5, vcc
	v_sub_u32_e32 v5, v4, v3
	v_cndmask_b32_e32 v4, v4, v5, vcc
	v_add_u32_e32 v5, 1, v1
	v_cmp_ge_u32_e32 vcc, v4, v3
	v_add_u32_e32 v4, 1, v6
	s_nop 0
	v_cndmask_b32_e32 v1, v1, v5, vcc
	v_mul_lo_u32 v5, v3, v1
	v_add_u32_e32 v3, v5, v3
	v_cmp_ne_u32_e32 vcc, v4, v3
	s_and_saveexec_b64 s[4:5], vcc
	s_xor_b64 s[4:5], exec, s[4:5]
	s_cbranch_execz .LBB0_856
	v_readlane_b32 s6, v253, 61
	v_readlane_b32 s7, v253, 62
	s_waitcnt lgkmcnt(0)
	s_nop 3
	global_load_dword v2, v0, s[6:7] sc1
	s_waitcnt vmcnt(0)
	v_cmp_le_u32_e32 vcc, v2, v1
	s_and_saveexec_b64 s[6:7], vcc
	s_cbranch_execz .LBB0_855
	s_mov_b32 s15, 1
	s_mov_b64 s[8:9], 0
	s_branch .LBB0_846

; __device__ __forceinline__ unsigned xb_ld(unsigned* p)              { return __hip_atomic_load(p, __ATOMIC_RELAXED, __HIP_MEMORY_SCOPE_AGENT); }
; #define XB_SPIN(cond, bar) do { unsigned _sp = 0; while (cond) { __builtin_amdgcn_s_sleep(1); \
;     if ((++_sp & 255u) == 0u) { if (xb_ld(&(bar)[XB_TMO])) break; if (_sp > XB_SPIN_CAP) { atomicAdd(&(bar)[XB_TMO], 1u); break; } } } } while (0)
; __device__ __forceinline__ void xcd_barrier(const XcdBarrier& b, bool local = false) {
;     ...
;             XB_SPIN(xb_ld(&bar[XB_XGEN(b.x)]) == gen, bar);
.LBB0_850:
	v_readlane_b32 s16, v253, 61
	v_readlane_b32 s17, v253, 62
	s_add_i32 s15, s15, 1
	s_mov_b64 s[44:45], -1
	s_nop 2
	global_load_dword v2, v0, s[16:17] sc1
	s_waitcnt vmcnt(0)
	v_cmp_gt_u32_e32 vcc, v2, v1
	s_orn2_b64 s[42:43], vcc, exec
	s_branch .LBB0_845
